# v35 + mLSTM scan: next-chunk global prefetch issued before the first MFMA block instead of after it
# speedup vs baseline: 1.0046x; 1.0046x over previous
.LBB0_208:
	s_waitcnt lgkmcnt(0)
	s_barrier
	s_waitcnt vmcnt(13)
	ds_write_b128 v189, v[0:3]
	s_waitcnt vmcnt(12)
	ds_write_b128 v189, v[4:7] offset:34816
	s_waitcnt vmcnt(11)
	v_alignbit_b32 v72, v9, v9, 16
	v_alignbit_b32 v73, v8, v8, 16
	v_cndmask_b32_e64 v80, v73, v11, s[2:3]
	v_cndmask_b32_e64 v81, v72, v10, s[2:3]
	ds_read_b128 v[72:75], v156
	v_alignbit_b32 v76, v11, v11, 16
	v_cndmask_b32_e64 v83, v76, v8, s[2:3]
	v_alignbit_b32 v77, v10, v10, 16
	v_lshlrev_b32_e32 v84, 16, v83
	v_and_b32_e32 v83, 0xffff0000, v83
	v_cndmask_b32_e64 v82, v77, v9, s[2:3]
	ds_read_b128 v[76:79], v156 offset:16
	s_waitcnt lgkmcnt(1)
	v_mul_f32_e32 v72, v72, v84
	v_mul_f32_e32 v73, v73, v83
	v_cvt_pk_bf16_f32 v72, v72, v73
	v_lshlrev_b32_e32 v73, 16, v82
	v_mul_f32_e32 v73, v74, v73
	v_and_b32_e32 v74, 0xffff0000, v82
	v_mul_f32_e32 v74, v75, v74
	v_cvt_pk_bf16_f32 v73, v73, v74
	v_lshlrev_b32_e32 v74, 16, v81
	v_and_b32_e32 v75, 0xffff0000, v81
	s_waitcnt lgkmcnt(0)
	v_mul_f32_e32 v74, v76, v74
	v_mul_f32_e32 v75, v77, v75
	v_cvt_pk_bf16_f32 v74, v74, v75
	v_lshlrev_b32_e32 v75, 16, v80
	v_mul_f32_e32 v75, v78, v75
	v_and_b32_e32 v76, 0xffff0000, v80
	v_mul_f32_e32 v76, v79, v76
	v_cvt_pk_bf16_f32 v75, v75, v76
	ds_write_b128 v190, v[72:75]
	s_waitcnt vmcnt(10)
	ds_write_b128 v192, v[12:15]
	s_waitcnt vmcnt(9)
	ds_write_b128 v192, v[16:19] offset:34816
	s_waitcnt vmcnt(8)
	v_alignbit_b32 v72, v21, v21, 16
	v_alignbit_b32 v73, v20, v20, 16
	v_cndmask_b32_e64 v80, v73, v23, s[2:3]
	v_cndmask_b32_e64 v81, v72, v22, s[2:3]
	ds_read_b128 v[72:75], v156
	v_alignbit_b32 v76, v23, v23, 16
	v_cndmask_b32_e64 v83, v76, v20, s[2:3]
	v_alignbit_b32 v77, v22, v22, 16
	v_lshlrev_b32_e32 v84, 16, v83
	v_and_b32_e32 v83, 0xffff0000, v83
	v_cndmask_b32_e64 v82, v77, v21, s[2:3]
	ds_read_b128 v[76:79], v156 offset:16
	s_waitcnt lgkmcnt(1)
	v_mul_f32_e32 v72, v72, v84
	v_mul_f32_e32 v73, v73, v83
	v_cvt_pk_bf16_f32 v72, v72, v73
	v_lshlrev_b32_e32 v73, 16, v82
	v_mul_f32_e32 v73, v74, v73
	v_and_b32_e32 v74, 0xffff0000, v82
	v_mul_f32_e32 v74, v75, v74
	v_cvt_pk_bf16_f32 v73, v73, v74
	v_lshlrev_b32_e32 v74, 16, v81
	v_and_b32_e32 v75, 0xffff0000, v81
	s_waitcnt lgkmcnt(0)
	v_mul_f32_e32 v74, v76, v74
	v_mul_f32_e32 v75, v77, v75
	v_cvt_pk_bf16_f32 v74, v74, v75
	v_lshlrev_b32_e32 v75, 16, v80
	v_mul_f32_e32 v75, v78, v75
	v_and_b32_e32 v76, 0xffff0000, v80
	v_mul_f32_e32 v76, v79, v76
	v_cvt_pk_bf16_f32 v75, v75, v76
	ds_write_b128 v193, v[72:75]
	s_waitcnt vmcnt(7)
	ds_write_b128 v194, v[24:27]
	s_waitcnt vmcnt(6)
	ds_write_b128 v194, v[28:31] offset:34816
	s_waitcnt vmcnt(5)
	v_alignbit_b32 v72, v33, v33, 16
	v_alignbit_b32 v73, v32, v32, 16
	v_cndmask_b32_e64 v80, v73, v35, s[2:3]
	v_cndmask_b32_e64 v81, v72, v34, s[2:3]
	ds_read_b128 v[72:75], v156
	v_alignbit_b32 v76, v35, v35, 16
	v_cndmask_b32_e64 v83, v76, v32, s[2:3]
	v_alignbit_b32 v77, v34, v34, 16
	v_lshlrev_b32_e32 v84, 16, v83
	v_and_b32_e32 v83, 0xffff0000, v83
	v_cndmask_b32_e64 v82, v77, v33, s[2:3]
	ds_read_b128 v[76:79], v156 offset:16
	s_waitcnt lgkmcnt(1)
	v_mul_f32_e32 v72, v72, v84
	v_mul_f32_e32 v73, v73, v83
	v_cvt_pk_bf16_f32 v72, v72, v73
	v_lshlrev_b32_e32 v73, 16, v82
	v_mul_f32_e32 v73, v74, v73
	v_and_b32_e32 v74, 0xffff0000, v82
	v_mul_f32_e32 v74, v75, v74
	v_cvt_pk_bf16_f32 v73, v73, v74
	v_lshlrev_b32_e32 v74, 16, v81
	v_and_b32_e32 v75, 0xffff0000, v81
	s_waitcnt lgkmcnt(0)
	v_mul_f32_e32 v74, v76, v74
	v_mul_f32_e32 v75, v77, v75
	v_cvt_pk_bf16_f32 v74, v74, v75
	v_lshlrev_b32_e32 v75, 16, v80
	v_mul_f32_e32 v75, v78, v75
	v_and_b32_e32 v76, 0xffff0000, v80
	v_mul_f32_e32 v76, v79, v76
	v_cvt_pk_bf16_f32 v75, v75, v76
	ds_write_b128 v195, v[72:75]
	s_waitcnt vmcnt(4)
	ds_write_b128 v196, v[36:39]
	s_waitcnt vmcnt(3)
	ds_write_b128 v196, v[40:43] offset:34816
	s_waitcnt vmcnt(2)
	v_alignbit_b32 v72, v45, v45, 16
	v_alignbit_b32 v73, v44, v44, 16
	v_cndmask_b32_e64 v80, v73, v47, s[2:3]
	v_cndmask_b32_e64 v81, v72, v46, s[2:3]
	ds_read_b128 v[72:75], v156
	v_alignbit_b32 v76, v47, v47, 16
	v_cndmask_b32_e64 v83, v76, v44, s[2:3]
	v_alignbit_b32 v77, v46, v46, 16
	v_lshlrev_b32_e32 v84, 16, v83
	v_and_b32_e32 v83, 0xffff0000, v83
	v_cndmask_b32_e64 v82, v77, v45, s[2:3]
	ds_read_b128 v[76:79], v156 offset:16
	s_waitcnt lgkmcnt(1)
	v_mul_f32_e32 v72, v72, v84
	v_mul_f32_e32 v73, v73, v83
	v_cvt_pk_bf16_f32 v72, v72, v73
	v_lshlrev_b32_e32 v73, 16, v82
	v_mul_f32_e32 v73, v74, v73
	v_and_b32_e32 v74, 0xffff0000, v82
	v_mul_f32_e32 v74, v75, v74
	v_cvt_pk_bf16_f32 v73, v73, v74
	v_lshlrev_b32_e32 v74, 16, v81
	v_and_b32_e32 v75, 0xffff0000, v81
	s_waitcnt lgkmcnt(0)
	v_mul_f32_e32 v74, v76, v74
	v_mul_f32_e32 v75, v77, v75
	v_cvt_pk_bf16_f32 v74, v74, v75
	v_lshlrev_b32_e32 v75, 16, v80
	v_mul_f32_e32 v75, v78, v75
	v_and_b32_e32 v76, 0xffff0000, v80
	v_mul_f32_e32 v76, v79, v76
	v_cvt_pk_bf16_f32 v75, v75, v76
	ds_write_b128 v197, v[72:75]
	s_waitcnt vmcnt(1)
	v_alignbit_b32 v72, v51, v51, 16
	v_alignbit_b32 v73, v50, v50, 16
	v_alignbit_b32 v74, v49, v49, 16
	v_alignbit_b32 v75, v48, v48, 16
	v_cndmask_b32_e64 v75, v75, v51, s[2:3]
	v_cndmask_b32_e64 v74, v74, v50, s[2:3]
	v_cndmask_b32_e64 v73, v73, v49, s[2:3]
	v_cndmask_b32_e64 v72, v72, v48, s[2:3]
	v_add_u32_e32 v76, v168, v188
	ds_write_b128 v76, v[72:75]
	s_waitcnt vmcnt(0)
	v_alignbit_b32 v72, v55, v55, 16
	v_alignbit_b32 v73, v54, v54, 16
	v_alignbit_b32 v74, v53, v53, 16
	v_alignbit_b32 v75, v52, v52, 16
	v_cndmask_b32_e64 v75, v75, v55, s[2:3]
	v_cndmask_b32_e64 v74, v74, v54, s[2:3]
	v_cndmask_b32_e64 v73, v73, v53, s[2:3]
	v_cndmask_b32_e64 v72, v72, v52, s[2:3]
	v_add_u32_e32 v76, v168, v191
	v_mov_b32_e32 v88, 0
	ds_write_b128 v76, v[72:75]
	s_mov_b32 s85, 0
	v_mov_b32_e32 v89, v88
	v_mov_b32_e32 v90, v88
	v_mov_b32_e32 v91, v88
	v_mov_b32_e32 v92, v88
	v_mov_b32_e32 v93, v88
	v_mov_b32_e32 v94, v88
	v_mov_b32_e32 v95, v88
	v_mov_b32_e32 v100, v88
	v_mov_b32_e32 v101, v88
	v_mov_b32_e32 v102, v88
	v_mov_b32_e32 v103, v88
	v_mov_b32_e32 v108, v88
	v_mov_b32_e32 v109, v88
	v_mov_b32_e32 v110, v88
	v_mov_b32_e32 v111, v88
	v_mov_b32_e32 v96, v88
	v_mov_b32_e32 v97, v88
	v_mov_b32_e32 v98, v88
	v_mov_b32_e32 v99, v88
	v_mov_b32_e32 v104, v88
	v_mov_b32_e32 v105, v88
	v_mov_b32_e32 v106, v88
	v_mov_b32_e32 v107, v88
	v_mov_b32_e32 v112, v88
	v_mov_b32_e32 v113, v88
	v_mov_b32_e32 v114, v88
	v_mov_b32_e32 v115, v88
	v_mov_b32_e32 v116, v88
	v_mov_b32_e32 v117, v88
	v_mov_b32_e32 v118, v88
	v_mov_b32_e32 v119, v88
	v_mov_b32_e32 v72, v88
	v_mov_b32_e32 v73, v88
	v_mov_b32_e32 v74, v88
	v_mov_b32_e32 v75, v88
	v_mov_b32_e32 v76, v88
	v_mov_b32_e32 v77, v88
	v_mov_b32_e32 v78, v88
	v_mov_b32_e32 v79, v88
	v_mov_b32_e32 v80, v88
	v_mov_b32_e32 v81, v88
	v_mov_b32_e32 v82, v88
	v_mov_b32_e32 v83, v88
	v_mov_b32_e32 v84, v88
	v_mov_b32_e32 v85, v88
	v_mov_b32_e32 v86, v88
	v_mov_b32_e32 v87, v88
	s_waitcnt lgkmcnt(0)
	s_barrier
	s_add_i32 s99, s84, 1
	s_cmp_ge_u32 s99, s95
	s_cbranch_scc1 .Lpf_skip
	s_lshl_b32 s100, s99, 7
	s_sub_i32 s101, s94, s100
	s_and_b64 s[86:87], s[2:3], exec
	s_cselect_b32 s100, s100, s101
	s_add_i32 s100, s100, s89
	s_ashr_i32 s101, s100, 7
	v_add_u32_e32 v0, s100, v148
	v_add_u32_e32 v12, s100, v150
	v_add_u32_e32 v24, s100, v151
	v_add_u32_e32 v36, s100, v152
	v_ashrrev_i32_e32 v1, 31, v0
	v_mad_i64_i32 v[8:9], s[86:87], s101, v149, v[136:137]
	v_ashrrev_i32_e32 v13, 31, v12
	v_mad_i64_i32 v[20:21], s[86:87], s101, v149, v[138:139]
	v_ashrrev_i32_e32 v25, 31, v24
	v_mad_i64_i32 v[32:33], s[86:87], s101, v149, v[140:141]
	v_ashrrev_i32_e32 v37, 31, v36
	v_mad_i64_i32 v[46:47], s[86:87], s101, v149, v[142:143]
	v_lshlrev_b64 v[0:1], 8, v[0:1]
	v_lshlrev_b64 v[44:45], 8, v[8:9]
	v_lshlrev_b64 v[12:13], 8, v[12:13]
	v_lshlrev_b64 v[52:53], 8, v[20:21]
	v_lshlrev_b64 v[24:25], 8, v[24:25]
	v_lshlrev_b64 v[32:33], 8, v[32:33]
	v_lshlrev_b64 v[36:37], 8, v[36:37]
	v_lshlrev_b64 v[46:47], 8, v[46:47]
	v_lshl_add_u64 v[2:3], v[128:129], 0, v[0:1]
	v_lshl_add_u64 v[4:5], v[130:131], 0, v[0:1]
	v_lshl_add_u64 v[8:9], v[132:133], 0, v[44:45]
	v_lshl_add_u64 v[14:15], v[128:129], 0, v[12:13]
	v_lshl_add_u64 v[16:17], v[130:131], 0, v[12:13]
	v_lshl_add_u64 v[20:21], v[132:133], 0, v[52:53]
	v_lshl_add_u64 v[26:27], v[128:129], 0, v[24:25]
	v_lshl_add_u64 v[28:29], v[130:131], 0, v[24:25]
	v_lshl_add_u64 v[32:33], v[132:133], 0, v[32:33]
	v_lshl_add_u64 v[38:39], v[128:129], 0, v[36:37]
	v_lshl_add_u64 v[40:41], v[130:131], 0, v[36:37]
	v_lshl_add_u64 v[46:47], v[132:133], 0, v[46:47]
	v_lshl_add_u64 v[48:49], v[144:145], 0, v[44:45]
	v_lshl_add_u64 v[52:53], v[144:145], 0, v[52:53]
	global_load_dwordx4 v[0:3], v[2:3], off
	s_nop 0
	global_load_dwordx4 v[4:7], v[4:5], off
	s_nop 0
	global_load_dwordx4 v[8:11], v[8:9], off
	s_nop 0
	global_load_dwordx4 v[12:15], v[14:15], off
	s_nop 0
	global_load_dwordx4 v[16:19], v[16:17], off
	s_nop 0
	global_load_dwordx4 v[20:23], v[20:21], off
	s_nop 0
	global_load_dwordx4 v[24:27], v[26:27], off
	s_nop 0
	global_load_dwordx4 v[28:31], v[28:29], off
	s_nop 0
	global_load_dwordx4 v[32:35], v[32:33], off
	s_nop 0
	global_load_dwordx4 v[36:39], v[38:39], off
	s_nop 0
	global_load_dwordx4 v[40:43], v[40:41], off
	s_nop 0
	global_load_dwordx4 v[44:47], v[46:47], off
	s_nop 0
	global_load_dwordx4 v[48:51], v[48:49], off
	s_nop 0
	global_load_dwordx4 v[52:55], v[52:53], off
	s_and_saveexec_b64 s[86:87], s[0:1]
	s_cbranch_execz .Lpf_215
	v_add_u32_e32 v120, s100, v153
	s_waitcnt lgkmcnt(0)
	v_ashrrev_i32_e32 v121, 31, v120
	v_readlane_b32 s100, v255, 10
	v_lshlrev_b64 v[120:121], 6, v[120:121]
	v_readlane_b32 s101, v255, 11
	s_nop 1
	v_lshl_add_u64 v[120:121], s[100:101], 0, v[120:121]
	global_load_dword v154, v[120:121], off
	global_load_dword v155, v[120:121], off offset:16

.Lpf_skip:
.LBB0_209:
	v_add_u32_e32 v202, s85, v214
	v_add_u32_e32 v219, s85, v213
	ds_read_b128 v[120:123], v202 offset:34816
	ds_read_b128 v[124:127], v219
	ds_read_b128 v[220:223], v219 offset:4352
	ds_read_b128 v[224:227], v219 offset:8704
	ds_read_b128 v[228:231], v219 offset:13056
	ds_read_b128 v[232:235], v202
	v_add_u32_e32 v236, s85, v212
	v_add_u32_e32 v219, 0x1dc00, v236
	v_add_u32_e32 v236, 0x1ed00, v236
	s_waitcnt lgkmcnt(4)
	v_mfma_f32_16x16x32_bf16 v[116:119], v[120:123], v[124:127], v[116:119]
	ds_read_b128 v[236:239], v236
	s_add_i32 s85, s85, 64
	s_cmpk_eq_i32 s85, 0x100
	s_waitcnt lgkmcnt(4)
	v_mfma_f32_16x16x32_bf16 v[112:115], v[120:123], v[220:223], v[112:115]
	s_waitcnt lgkmcnt(3)
	v_mfma_f32_16x16x32_bf16 v[104:107], v[120:123], v[224:227], v[104:107]
	s_waitcnt lgkmcnt(2)
	v_mfma_f32_16x16x32_bf16 v[96:99], v[120:123], v[228:231], v[96:99]
	ds_read_b128 v[120:123], v219
	s_waitcnt lgkmcnt(0)
	v_mfma_f32_16x16x32_bf16 v[84:87], v[232:235], v[120:123], v[84:87]
	v_mfma_f32_16x16x32_bf16 v[80:83], v[232:235], v[236:239], v[80:83]
	ds_read_b128 v[232:235], v202 offset:39168
	s_waitcnt lgkmcnt(0)
	v_mfma_f32_16x16x32_bf16 v[108:111], v[232:235], v[124:127], v[108:111]
	ds_read_b128 v[124:127], v202 offset:4352
	v_mfma_f32_16x16x32_bf16 v[100:103], v[232:235], v[220:223], v[100:103]
	v_mfma_f32_16x16x32_bf16 v[92:95], v[232:235], v[224:227], v[92:95]
	v_mfma_f32_16x16x32_bf16 v[88:91], v[232:235], v[228:231], v[88:91]
	s_waitcnt lgkmcnt(0)
	v_mfma_f32_16x16x32_bf16 v[76:79], v[124:127], v[120:123], v[76:79]
	v_mfma_f32_16x16x32_bf16 v[72:75], v[124:127], v[236:239], v[72:75]
	s_cbranch_scc0 .LBB0_209
	ds_read_b128 v[120:123], v169
	ds_read_b128 v[124:127], v169 offset:16
	ds_read_b128 v[220:223], v169 offset:32
	ds_read_b128 v[224:227], v169 offset:48
	ds_read_b128 v[228:231], v170
	ds_read_b128 v[232:235], v170 offset:16
	ds_read_b128 v[236:239], v170 offset:32
	ds_read_b128 v[240:243], v170 offset:48
	s_waitcnt lgkmcnt(7)
	v_lshlrev_b32_e32 v202, 16, v120
	v_and_b32_e32 v120, 0xffff0000, v120
	s_waitcnt lgkmcnt(3)
	v_mul_f32_e32 v120, v229, v120
	v_fmac_f32_e32 v120, v228, v202
	v_lshlrev_b32_e32 v202, 16, v121
	v_fmac_f32_e32 v120, v230, v202
	v_and_b32_e32 v121, 0xffff0000, v121
	v_fmac_f32_e32 v120, v231, v121
	v_lshlrev_b32_e32 v121, 16, v122
	s_waitcnt lgkmcnt(2)
	v_fmac_f32_e32 v120, v232, v121
	v_and_b32_e32 v121, 0xffff0000, v122
	v_fmac_f32_e32 v120, v233, v121
	v_lshlrev_b32_e32 v121, 16, v123
	v_fmac_f32_e32 v120, v234, v121
	v_and_b32_e32 v121, 0xffff0000, v123
	v_fmac_f32_e32 v120, v235, v121
	v_and_b32_e32 v121, 0xffff0000, v124
	v_add_f32_e32 v202, 0, v120
	v_lshlrev_b32_e32 v120, 16, v124
	s_waitcnt lgkmcnt(1)
	v_mul_f32_e32 v124, v237, v121
	v_fmac_f32_e32 v124, v236, v120
	v_lshlrev_b32_e32 v120, 16, v125
	v_fmac_f32_e32 v124, v238, v120
	v_and_b32_e32 v120, 0xffff0000, v125
	v_fmac_f32_e32 v124, v239, v120
	v_lshlrev_b32_e32 v120, 16, v126
	s_waitcnt lgkmcnt(0)
	v_fmac_f32_e32 v124, v240, v120
	v_and_b32_e32 v120, 0xffff0000, v126
	v_fmac_f32_e32 v124, v241, v120
	v_lshlrev_b32_e32 v120, 16, v127
	v_fmac_f32_e32 v124, v242, v120
	v_and_b32_e32 v120, 0xffff0000, v127
	v_fmac_f32_e32 v124, v243, v120
	ds_read_b128 v[120:123], v170 offset:64
	v_add_f32_e32 v202, v202, v124
	ds_read_b128 v[124:127], v170 offset:80
	v_lshlrev_b32_e32 v219, 16, v220
	v_and_b32_e32 v220, 0xffff0000, v220
	s_waitcnt lgkmcnt(1)
	v_mul_f32_e32 v220, v121, v220
	v_fmac_f32_e32 v220, v120, v219
	v_lshlrev_b32_e32 v120, 16, v221
	v_fmac_f32_e32 v220, v122, v120
	v_and_b32_e32 v120, 0xffff0000, v221
	v_fmac_f32_e32 v220, v123, v120
	v_lshlrev_b32_e32 v120, 16, v222
	s_waitcnt lgkmcnt(0)
	v_fmac_f32_e32 v220, v124, v120
	v_and_b32_e32 v120, 0xffff0000, v222
	v_fmac_f32_e32 v220, v125, v120
	v_lshlrev_b32_e32 v120, 16, v223
	v_fmac_f32_e32 v220, v126, v120
	v_and_b32_e32 v120, 0xffff0000, v223
	v_fmac_f32_e32 v220, v127, v120
	ds_read_b128 v[120:123], v170 offset:96
	ds_read_b128 v[124:127], v170 offset:112
	v_add_f32_e32 v202, v202, v220
	v_and_b32_e32 v220, 0xffff0000, v224
	v_lshlrev_b32_e32 v219, 16, v224
	s_waitcnt lgkmcnt(1)
	v_mul_f32_e32 v121, v121, v220
	v_fmac_f32_e32 v121, v120, v219
	v_lshlrev_b32_e32 v120, 16, v225
	v_fmac_f32_e32 v121, v122, v120
	v_and_b32_e32 v120, 0xffff0000, v225
	v_fmac_f32_e32 v121, v123, v120
	v_lshlrev_b32_e32 v120, 16, v226
	s_waitcnt lgkmcnt(0)
	v_fmac_f32_e32 v121, v124, v120
	v_and_b32_e32 v120, 0xffff0000, v226
	v_fmac_f32_e32 v121, v125, v120
	v_lshlrev_b32_e32 v120, 16, v227
	v_fmac_f32_e32 v121, v126, v120
	v_and_b32_e32 v120, 0xffff0000, v227
	v_fmac_f32_e32 v121, v127, v120
	v_add_f32_e32 v120, v202, v121
	ds_bpermute_b32 v121, v171, v120
	s_waitcnt lgkmcnt(0)
	v_add_f32_e32 v120, v120, v121
	ds_bpermute_b32 v121, v172, v120
	s_and_saveexec_b64 s[86:87], s[6:7]
	s_cbranch_execz .LBB0_212
	s_waitcnt lgkmcnt(0)
	v_add_f32_e32 v120, v120, v121
	ds_write_b32 v173, v120
.LBB0_212:
	s_or_b64 exec, exec, s[86:87]
	s_add_i32 s85, s84, 1
.LBB0_216:
	v_add_u32_e32 v120, s96, v174
	ds_read_b128 v[124:127], v120
	ds_read_b32 v202, v198
	s_waitcnt lgkmcnt(0)
	v_sub_f32_e32 v121, v124, v202
	v_sub_f32_e32 v122, v125, v202
	v_mul_f32_e32 v121, 0x3fb8aa3b, v121
	v_mul_f32_e32 v122, 0x3fb8aa3b, v122
	v_exp_f32_e32 v219, v121
	v_exp_f32_e32 v220, v122
	ds_read_b128 v[120:123], v120 offset:64
	v_sub_f32_e32 v221, v126, v202
	v_mul_f32_e32 v221, 0x3fb8aa3b, v221
	v_sub_f32_e32 v222, v127, v202
	v_exp_f32_e32 v221, v221
	v_mul_f32_e32 v222, 0x3fb8aa3b, v222
	s_waitcnt lgkmcnt(0)
	v_sub_f32_e32 v223, v120, v202
	v_exp_f32_e32 v222, v222
	v_mul_f32_e32 v223, 0x3fb8aa3b, v223
	v_sub_f32_e32 v224, v121, v202
	v_cndmask_b32_e64 v219, v219, 0, s[18:19]
	v_exp_f32_e32 v223, v223
	v_mul_f32_e32 v224, 0x3fb8aa3b, v224
	v_sub_f32_e32 v225, v122, v202
	v_cndmask_b32_e64 v220, 0, v220, s[20:21]
	v_fma_f32 v227, v116, v219, 0
	v_exp_f32_e32 v224, v224
	v_mul_f32_e32 v225, 0x3fb8aa3b, v225
	v_sub_f32_e32 v202, v123, v202
	v_fmac_f32_e32 v227, v117, v220
	v_cndmask_b32_e64 v221, v221, 0, s[22:23]
	v_exp_f32_e32 v225, v225
	v_mul_f32_e32 v202, 0x3fb8aa3b, v202
	v_fmac_f32_e32 v227, v118, v221
	v_cndmask_b32_e64 v222, v222, 0, s[24:25]
	v_exp_f32_e32 v202, v202
	v_fmac_f32_e32 v227, v119, v222
	v_cndmask_b32_e64 v223, v223, 0, s[26:27]
	v_fmac_f32_e32 v227, v108, v223
	v_cndmask_b32_e64 v224, v224, 0, s[28:29]
	v_fmac_f32_e32 v227, v109, v224
	v_cndmask_b32_e64 v225, v225, 0, s[30:31]
	v_fmac_f32_e32 v227, v110, v225
	v_cndmask_b32_e64 v226, v202, 0, s[34:35]
	v_fmac_f32_e32 v227, v111, v226
	ds_bpermute_b32 v202, v175, v227
	s_waitcnt lgkmcnt(0)
	v_add_f32_e32 v227, v227, v202
	ds_bpermute_b32 v228, v176, v227
	s_and_saveexec_b64 s[86:87], s[8:9]
	s_cbranch_execz .LBB0_218
	s_waitcnt lgkmcnt(0)
	v_add_f32_e32 v202, v227, v228
	ds_write_b32 v199, v202

	.amdhsa_kernel _Z10fwd_kernel6Params
		.amdhsa_group_segment_fixed_size 0
		.amdhsa_private_segment_fixed_size 0
		.amdhsa_kernarg_size 472
		.amdhsa_user_sgpr_count 2
		.amdhsa_user_sgpr_dispatch_ptr 0
		.amdhsa_user_sgpr_queue_ptr 0
		.amdhsa_user_sgpr_kernarg_segment_ptr 1
		.amdhsa_user_sgpr_dispatch_id 0
		.amdhsa_user_sgpr_kernarg_preload_length 0
		.amdhsa_user_sgpr_kernarg_preload_offset 0
		.amdhsa_user_sgpr_private_segment_size 0
		.amdhsa_uses_dynamic_stack 0
		.amdhsa_enable_private_segment 0
		.amdhsa_system_sgpr_workgroup_id_x 1
		.amdhsa_system_sgpr_workgroup_id_y 0
		.amdhsa_system_sgpr_workgroup_id_z 0
		.amdhsa_system_sgpr_workgroup_info 0
		.amdhsa_system_vgpr_workitem_id 2
		.amdhsa_next_free_vgpr 256
		.amdhsa_next_free_sgpr 102
		.amdhsa_accum_offset 256
		.amdhsa_reserve_vcc 1
		.amdhsa_float_round_mode_32 0
		.amdhsa_float_round_mode_16_64 0
		.amdhsa_float_denorm_mode_32 3
		.amdhsa_float_denorm_mode_16_64 3
		.amdhsa_dx10_clamp 1
		.amdhsa_ieee_mode 1
		.amdhsa_fp16_overflow 0
		.amdhsa_tg_split 0
		.amdhsa_exception_fp_ieee_invalid_op 0
		.amdhsa_exception_fp_denorm_src 0
		.amdhsa_exception_fp_ieee_div_zero 0
		.amdhsa_exception_fp_ieee_overflow 0
		.amdhsa_exception_fp_ieee_underflow 0
		.amdhsa_exception_fp_ieee_inexact 0
		.amdhsa_exception_int_div_zero 0
	.end_amdhsa_kernel

amdhsa.kernels:
  - .agpr_count:     0
    .args:
      - .offset:         0
        .size:           216
        .value_kind:     by_value
      - .offset:         216
        .size:           4
        .value_kind:     hidden_block_count_x
      - .offset:         220
        .size:           4
        .value_kind:     hidden_block_count_y
      - .offset:         224
        .size:           4
        .value_kind:     hidden_block_count_z
      - .offset:         228
        .size:           2
        .value_kind:     hidden_group_size_x
      - .offset:         230
        .size:           2
        .value_kind:     hidden_group_size_y
      - .offset:         232
        .size:           2
        .value_kind:     hidden_group_size_z
      - .offset:         234
        .size:           2
        .value_kind:     hidden_remainder_x
      - .offset:         236
        .size:           2
        .value_kind:     hidden_remainder_y
      - .offset:         238
        .size:           2
        .value_kind:     hidden_remainder_z
      - .offset:         256
        .size:           8
        .value_kind:     hidden_global_offset_x
      - .offset:         264
        .size:           8
        .value_kind:     hidden_global_offset_y
      - .offset:         272
        .size:           8
        .value_kind:     hidden_global_offset_z
      - .offset:         280
        .size:           2
        .value_kind:     hidden_grid_dims
      - .offset:         304
        .size:           8
        .value_kind:     hidden_multigrid_sync_arg
      - .offset:         336
        .size:           4
        .value_kind:     hidden_dynamic_lds_size
    .group_segment_fixed_size: 0
    .kernarg_segment_align: 8
    .kernarg_segment_size: 472
    .language:       OpenCL C
    .language_version:
      - 2
      - 0
    .max_flat_workgroup_size: 512
    .name:           _Z10fwd_kernel6Params
    .private_segment_fixed_size: 0
    .sgpr_count:     108
    .sgpr_spill_count: 126
    .symbol:         _Z10fwd_kernel6Params.kd
    .uniform_work_group_size: 1
    .uses_dynamic_stack: false
    .vgpr_count:     256
    .vgpr_spill_count: 0
    .wavefront_size: 64
